# baseline (speedup 1.0000x reference)
; __device__ void attn_item(const Params& p, int item, char* smem, volatile int* flags) {
;     ...
;       const int row = tid >> 2, qu = tid & 3;
;       const size_t tk = (size_t)b * SEQ + (size_t)kt * 64 + row;
;       const uint4* ksrc = (const uint4*)(p.proj + tk * NPROJ + OFF_K + h * 128 + qu * 32);
;       const uint4* vsrc = (const uint4*)(p.proj + tk * NPROJ + OFF_V + h * 128 + qu * 32);
;       float f[32];
;       float ss = 0.f;
; #pragma unroll
;       for (int i = 0; i < 4; ++i) unpack8(ksrc[i], f + i * 8);
; #pragma unroll
;       for (int i = 0; i < 32; ++i) ss += f[i] * f[i];
;       ss += __shfl_xor(ss, 1);
;       ss += __shfl_xor(ss, 2);
;       const float inv = rsqrtf(ss * (1.f / 128.f) + 1e-6f);
;       const float* g = p.sb_k_norm + qu * 32;
;     ...
;       for (int i = 0; i < 4; ++i) {
;         uint4 v = vsrc[i];
.LBB0_220:
	s_or_b64 exec, exec, s[0:1]
	s_cmp_gt_i32 s2, -1
	s_cselect_b64 s[0:1], -1, 0
	s_and_b64 s[64:65], s[96:97], s[0:1]
	s_and_saveexec_b64 s[0:1], s[64:65]
	s_cbranch_execz .LBB0_222
	v_readlane_b32 s12, v253, 39
	s_lshl_b64 s[4:5], s[2:3], 6
	v_readlane_b32 s16, v253, 43
	v_readlane_b32 s17, v253, 44
	v_lshl_add_u64 v[64:65], v[132:133], 0, s[4:5]
	v_readlane_b32 s13, v253, 40
	v_mov_b64_e32 v[66:67], s[16:17]
	v_mad_u64_u32 v[66:67], s[4:5], v64, s86, v[66:67]
	v_mad_i32_i24 v67, v65, s86, v67
	s_lshl_b32 s4, s78, 1
	s_mov_b32 s5, s3
	v_lshl_add_u64 v[64:65], v[66:67], 0, s[4:5]
	v_lshl_add_u64 v[64:65], v[64:65], 0, v[128:129]
	global_load_dwordx4 v[162:165], v[64:65], off offset:2096
	global_load_dwordx4 v[66:69], v[64:65], off offset:2080
	global_load_dwordx4 v[70:73], v[64:65], off offset:2064
	global_load_dwordx4 v[74:77], v[64:65], off offset:2048
	s_mov_b64 s[4:5], 0x1000
	v_lshl_add_u64 v[228:229], v[64:65], 0, s[4:5]
	global_load_dwordx4 v[232:235], v[228:229], off
	global_load_dwordx4 v[236:239], v[228:229], off offset:48
	global_load_dwordx4 v[240:243], v[228:229], off offset:32
	global_load_dwordx4 v[244:247], v[228:229], off offset:16
	v_readlane_b32 s14, v253, 41
	v_readlane_b32 s15, v253, 42
	v_readlane_b32 s18, v253, 45
	v_readlane_b32 s19, v253, 46
	v_readlane_b32 s20, v253, 47
	v_readlane_b32 s21, v253, 48
	v_readlane_b32 s22, v253, 49
	v_readlane_b32 s23, v253, 50
	v_readlane_b32 s24, v253, 51
	v_readlane_b32 s25, v253, 52
	v_readlane_b32 s26, v253, 53
	v_readlane_b32 s27, v253, 54
	s_waitcnt vmcnt(4)
	v_lshlrev_b32_e32 v78, 16, v68
	v_lshlrev_b32_e32 v82, 16, v70
	v_lshlrev_b32_e32 v90, 16, v74
	v_and_b32_e32 v91, 0xffff0000, v74
	v_lshlrev_b32_e32 v92, 16, v75
	v_and_b32_e32 v93, 0xffff0000, v75
	v_lshlrev_b32_e32 v94, 16, v76
	v_and_b32_e32 v95, 0xffff0000, v76
	v_lshlrev_b32_e32 v138, 16, v77
	v_and_b32_e32 v139, 0xffff0000, v77
	v_and_b32_e32 v83, 0xffff0000, v70
	v_lshlrev_b32_e32 v84, 16, v71
	v_and_b32_e32 v85, 0xffff0000, v71
	v_lshlrev_b32_e32 v86, 16, v72
	v_and_b32_e32 v87, 0xffff0000, v72
	v_lshlrev_b32_e32 v88, 16, v73
	v_and_b32_e32 v89, 0xffff0000, v73
	v_lshlrev_b32_e32 v74, 16, v66
	v_and_b32_e32 v75, 0xffff0000, v66
	v_lshlrev_b32_e32 v76, 16, v67
	v_and_b32_e32 v77, 0xffff0000, v67
	v_and_b32_e32 v79, 0xffff0000, v68
	v_lshlrev_b32_e32 v80, 16, v69
	v_and_b32_e32 v81, 0xffff0000, v69
	v_lshlrev_b32_e32 v66, 16, v162
	v_and_b32_e32 v67, 0xffff0000, v162
	v_lshlrev_b32_e32 v68, 16, v163
	v_and_b32_e32 v69, 0xffff0000, v163
	v_lshlrev_b32_e32 v73, 16, v164
	v_and_b32_e32 v72, 0xffff0000, v164
	v_lshlrev_b32_e32 v71, 16, v165
	v_and_b32_e32 v70, 0xffff0000, v165
	global_load_dwordx4 v[162:165], v[136:137], off offset:48
	global_load_dwordx4 v[168:171], v[136:137], off offset:32
	global_load_dwordx4 v[172:175], v[136:137], off offset:16
	global_load_dwordx4 v[176:179], v[136:137], off
	global_load_dwordx4 v[180:183], v[136:137], off offset:112
	global_load_dwordx4 v[184:187], v[136:137], off offset:96
	global_load_dwordx4 v[188:191], v[136:137], off offset:80
	global_load_dwordx4 v[192:195], v[136:137], off offset:64
	v_pk_mul_f32 v[206:207], v[90:91], v[90:91]
	v_pk_mul_f32 v[204:205], v[92:93], v[92:93]
	v_add_f32_e32 v149, v206, v207
	v_add_f32_e32 v149, v149, v204
	v_pk_mul_f32 v[202:203], v[94:95], v[94:95]
	v_add_f32_e32 v149, v205, v149
	v_add_f32_e32 v149, v202, v149
	v_pk_mul_f32 v[200:201], v[138:139], v[138:139]
	v_add_f32_e32 v149, v203, v149
	v_add_f32_e32 v149, v200, v149
	v_pk_mul_f32 v[214:215], v[82:83], v[82:83]
	v_add_f32_e32 v149, v201, v149
	v_add_f32_e32 v149, v214, v149
	v_pk_mul_f32 v[212:213], v[84:85], v[84:85]
	v_add_f32_e32 v149, v215, v149
	v_add_f32_e32 v149, v212, v149
	v_pk_mul_f32 v[210:211], v[86:87], v[86:87]
	v_add_f32_e32 v149, v213, v149
	v_add_f32_e32 v149, v210, v149
	v_pk_mul_f32 v[208:209], v[88:89], v[88:89]
	v_add_f32_e32 v149, v211, v149
	v_add_f32_e32 v149, v208, v149
	v_pk_mul_f32 v[222:223], v[74:75], v[74:75]
	v_add_f32_e32 v149, v209, v149
	v_add_f32_e32 v149, v222, v149
	v_pk_mul_f32 v[220:221], v[76:77], v[76:77]
	v_add_f32_e32 v149, v223, v149
	v_add_f32_e32 v149, v220, v149
	v_pk_mul_f32 v[218:219], v[78:79], v[78:79]
	v_add_f32_e32 v149, v221, v149
	v_add_f32_e32 v149, v218, v149
	v_pk_mul_f32 v[216:217], v[80:81], v[80:81]
	v_add_f32_e32 v149, v219, v149
	v_add_f32_e32 v149, v216, v149
	v_pk_mul_f32 v[226:227], v[66:67], v[66:67]
	v_add_f32_e32 v149, v217, v149
	v_add_f32_e32 v149, v226, v149
	v_pk_mul_f32 v[224:225], v[68:69], v[68:69]
	v_add_f32_e32 v149, v227, v149
	v_add_f32_e32 v149, v224, v149
	v_pk_mul_f32 v[196:197], v[72:73], v[72:73]
	v_add_f32_e32 v149, v225, v149
	v_add_f32_e32 v149, v197, v149
	v_pk_mul_f32 v[198:199], v[70:71], v[70:71]
	v_add_f32_e32 v149, v196, v149
	v_add_f32_e32 v149, v199, v149
	v_add_f32_e32 v149, v198, v149
	ds_bpermute_b32 v166, v131, v149
	s_waitcnt lgkmcnt(0)
; __device__ void attn_item(const Params& p, int item, char* smem, volatile int* flags) {
;     ...
;       ss += __shfl_xor(ss, 1);
;       ss += __shfl_xor(ss, 2);
;       const float inv = rsqrtf(ss * (1.f / 128.f) + 1e-6f);
;       const float* g = p.sb_k_norm + qu * 32;
; #pragma unroll
;       for (int i = 0; i < 4; ++i) {
;         float o8[8];
; #pragma unroll
;         for (int j = 0; j < 8; ++j) o8[j] = f[i * 8 + j] * inv * g[i * 8 + j];
;         *(uint4*)(Ks + row * 136 + qu * 32 + i * 8) = pack8(o8);
;       }
; #pragma unroll
;       for (int i = 0; i < 4; ++i) {
;         uint4 v = vsrc[i];
;         u32 wds[4] = {v.x, v.y, v.z, v.w};
; #pragma unroll
;         for (int j = 0; j < 4; ++j) {
;           Vt[(qu * 32 + i * 8 + j * 2 + 0) * 72 + row] = (u16)(wds[j] & 0xFFFFu);
;           Vt[(qu * 32 + i * 8 + j * 2 + 1) * 72 + row] = (u16)(wds[j] >> 16);
;         }
	v_add_f32_e32 v149, v149, v166
	ds_bpermute_b32 v166, v146, v149
	s_waitcnt lgkmcnt(0)
	v_add_f32_e32 v149, v149, v166
	v_fmamk_f32 v149, v149, 0x3c000000, v140
	v_cmp_gt_f32_e64 s[4:5], s10, v149
	v_mul_f32_e32 v166, 0x4b800000, v149
	s_nop 0
	v_cndmask_b32_e64 v149, v149, v166, s[4:5]
	v_rsq_f32_e32 v149, v149
	s_nop 0
	v_mul_f32_e32 v166, 0x45800000, v149
	v_cndmask_b32_e64 v166, v149, v166, s[4:5]
	v_pk_mul_f32 v[74:75], v[166:167], v[74:75] op_sel_hi:[0,1]
	v_pk_mul_f32 v[76:77], v[166:167], v[76:77] op_sel_hi:[0,1]
	v_pk_mul_f32 v[78:79], v[166:167], v[78:79] op_sel_hi:[0,1]
	v_pk_mul_f32 v[80:81], v[166:167], v[80:81] op_sel_hi:[0,1]
	v_pk_mul_f32 v[90:91], v[166:167], v[90:91] op_sel_hi:[0,1]
	v_pk_mul_f32 v[92:93], v[166:167], v[92:93] op_sel_hi:[0,1]
	v_pk_mul_f32 v[94:95], v[166:167], v[94:95] op_sel_hi:[0,1]
	v_pk_mul_f32 v[138:139], v[166:167], v[138:139] op_sel_hi:[0,1]
	v_pk_mul_f32 v[82:83], v[166:167], v[82:83] op_sel_hi:[0,1]
	v_pk_mul_f32 v[84:85], v[166:167], v[84:85] op_sel_hi:[0,1]
	v_pk_mul_f32 v[86:87], v[166:167], v[86:87] op_sel_hi:[0,1]
	v_pk_mul_f32 v[88:89], v[166:167], v[88:89] op_sel_hi:[0,1]
	s_waitcnt vmcnt(0)
	v_pk_mul_f32 v[74:75], v[192:193], v[74:75]
	v_pk_mul_f32 v[76:77], v[194:195], v[76:77]
	v_pk_mul_f32 v[78:79], v[78:79], v[188:189]
	v_pk_mul_f32 v[80:81], v[80:81], v[190:191]
	v_pk_mul_f32 v[66:67], v[166:167], v[66:67] op_sel_hi:[0,1]
	v_pk_mul_f32 v[68:69], v[166:167], v[68:69] op_sel_hi:[0,1]
	v_pk_mul_f32 v[72:73], v[166:167], v[72:73] op_sel_hi:[0,1]
	v_pk_mul_f32 v[70:71], v[166:167], v[70:71] op_sel_hi:[0,1]
	v_pk_mul_f32 v[90:91], v[176:177], v[90:91]
	v_pk_mul_f32 v[92:93], v[178:179], v[92:93]
	v_pk_mul_f32 v[94:95], v[172:173], v[94:95]
	v_pk_mul_f32 v[138:139], v[174:175], v[138:139]
	v_pk_mul_f32 v[82:83], v[168:169], v[82:83]
	v_pk_mul_f32 v[84:85], v[170:171], v[84:85]
	v_pk_mul_f32 v[86:87], v[162:163], v[86:87]
	v_pk_mul_f32 v[88:89], v[164:165], v[88:89]
	v_cvt_pk_bf16_f32 v74, v74, v75
	v_cvt_pk_bf16_f32 v75, v76, v77
	v_cvt_pk_bf16_f32 v76, v78, v79
	v_cvt_pk_bf16_f32 v77, v80, v81
	v_pk_mul_f32 v[66:67], v[66:67], v[184:185]
	v_pk_mul_f32 v[68:69], v[68:69], v[186:187]
	v_pk_mul_f32 v[72:73], v[72:73], v[180:181] op_sel:[1,0] op_sel_hi:[0,1]
	v_pk_mul_f32 v[70:71], v[70:71], v[182:183] op_sel:[1,0] op_sel_hi:[0,1]
	s_mov_b64 s[4:5], 0x1000
	v_cvt_pk_bf16_f32 v90, v90, v91
	v_cvt_pk_bf16_f32 v91, v92, v93
	v_cvt_pk_bf16_f32 v92, v94, v95
	v_cvt_pk_bf16_f32 v93, v138, v139
	v_cvt_pk_bf16_f32 v82, v82, v83
	v_cvt_pk_bf16_f32 v83, v84, v85
	v_cvt_pk_bf16_f32 v84, v86, v87
	v_cvt_pk_bf16_f32 v85, v88, v89
	ds_write_b128 v147, v[74:77] offset:34848
	v_cvt_pk_bf16_f32 v66, v66, v67
	v_cvt_pk_bf16_f32 v67, v68, v69
	v_cvt_pk_bf16_f32 v68, v72, v73
	v_cvt_pk_bf16_f32 v69, v70, v71
	v_lshl_add_u64 v[76:77], v[64:65], 0, s[4:5]
	v_add_co_u32_e64 v64, s[4:5], s85, v64
	ds_write_b128 v147, v[90:93] offset:34816
	ds_write_b128 v147, v[82:85] offset:34832
	ds_write_b128 v147, v[66:69] offset:34864
	v_addc_co_u32_e64 v65, s[4:5], 0, v65, s[4:5]
	v_mov_b64_e32 v[72:73], v[232:233]
	v_mov_b64_e32 v[74:75], v[234:235]
	v_mov_b64_e32 v[64:65], v[236:237]
	v_mov_b64_e32 v[66:67], v[238:239]
	v_mov_b64_e32 v[68:69], v[240:241]
	v_mov_b64_e32 v[70:71], v[242:243]
	v_mov_b64_e32 v[76:77], v[244:245]
	v_mov_b64_e32 v[78:79], v[246:247]
	s_waitcnt vmcnt(3)
	ds_write_b16 v135, v72 offset:53248
	ds_write_b16_d16_hi v135, v72 offset:53392
	ds_write_b16 v135, v73 offset:53536
	ds_write_b16_d16_hi v135, v73 offset:53680
	ds_write_b16 v135, v74 offset:53824
	ds_write_b16_d16_hi v135, v74 offset:53968
	ds_write_b16 v135, v75 offset:54112
	ds_write_b16_d16_hi v135, v75 offset:54256
	s_waitcnt vmcnt(0)
	ds_write_b16 v135, v76 offset:54400
	ds_write_b16_d16_hi v135, v76 offset:54544
	ds_write_b16 v135, v77 offset:54688
	ds_write_b16_d16_hi v135, v77 offset:54832
	ds_write_b16 v135, v78 offset:54976
	ds_write_b16_d16_hi v135, v78 offset:55120
	ds_write_b16 v135, v79 offset:55264
	ds_write_b16_d16_hi v135, v79 offset:55408
	ds_write_b16 v135, v68 offset:55552
	ds_write_b16_d16_hi v135, v68 offset:55696
	ds_write_b16 v135, v69 offset:55840
	ds_write_b16_d16_hi v135, v69 offset:55984
	ds_write_b16 v135, v70 offset:56128
	ds_write_b16_d16_hi v135, v70 offset:56272
	ds_write_b16 v135, v71 offset:56416
	ds_write_b16_d16_hi v135, v71 offset:56560
	ds_write_b16 v135, v64 offset:56704
	ds_write_b16_d16_hi v135, v64 offset:56848
	ds_write_b16 v135, v65 offset:56992
	ds_write_b16_d16_hi v135, v65 offset:57136
	ds_write_b16 v135, v66 offset:57280
	ds_write_b16_d16_hi v135, v66 offset:57424
	ds_write_b16 v135, v67 offset:57568
	ds_write_b16_d16_hi v135, v67 offset:57712
